# v26: v25 + P2 sample-row pooling items handled by waves 1536..1791 instead of the longest low waves
# speedup vs baseline: 1.0040x; 1.0017x over previous
; __global__ void __launch_bounds__(512, 2) mega_fwd(Args args) {
;     ...
;         for (int it = gw; it < 4 * (NS / 2); it += NGW) {
;             const int g = it & 3, rp = it >> 2, row = T + 2 * rp + (lane >> 5), c0 = g * 256 + (lane & 31) * 8, w = 2 << g;
;             float acc[8], cur[8];
; #pragma unroll
;             for (int e = 0; e < 8; ++e) { acc[e] = 0.f; cur[e] = 0.f; }
;             const int b = (row - T) >> 2, tq = (row - T) & 3;
.LBB0_313:
	s_cmpk_lt_i32 s12, 0x100
	s_cselect_b64 s[4:5], -1, 0
	s_sub_i32 s100, s12, 0x600
	s_cmpk_gt_u32 s100, 0xff
	s_cbranch_scc1 .LBB0_322
	v_lshrrev_b32_e32 v0, 5, v192
	s_load_dwordx2 s[6:7], s[8:9], 0xf8
	v_or_b32_e32 v34, 0x4000, v0
	v_lshlrev_b32_e32 v0, 3, v193
	v_and_b32_e32 v0, 0xf8, v0
	s_bfe_u32 s10, s39, 0x20006
	v_lshl_or_b32 v0, s10, 8, v0
	v_mov_b32_e32 v9, 0
	v_lshlrev_b32_e32 v8, 1, v0
	s_waitcnt lgkmcnt(0)
	v_lshl_add_u64 v[2:3], s[6:7], 0, v[8:9]
	s_mov_b64 s[6:7], 0x15d00000
	s_lshl_b32 s13, 2, s10
	v_lshl_add_u64 v[10:11], v[2:3], 0, s[6:7]
	s_mov_b64 s[6:7], 0x22100000
	v_cvt_f32_ubyte0_e32 v35, s13
	v_lshl_add_u64 v[12:13], v[2:3], 0, s[6:7]
	s_add_i32 s13, s13, -1
	v_lshlrev_b32_e32 v14, 2, v0
	s_mov_b32 s15, s100
	s_branch .LBB0_316
